# v20
# speedup vs baseline: 1.0203x; 1.0011x over previous
.LBB0_417:
	s_mov_b32 s22, 0x80
	s_mov_b32 s23, 0
	v_lshl_add_u64 v[124:125], v[50:51], 0, s[22:23]
	v_lshl_add_u64 v[126:127], v[52:53], 0, s[22:23]
	global_load_dwordx4 v[84:87], v[124:125], off
	global_load_dwordx4 v[80:83], v[124:125], off offset:16
	global_load_dwordx4 v[76:79], v[126:127], off
	global_load_dwordx4 v[72:75], v[126:127], off offset:16
	s_waitcnt vmcnt(4) lgkmcnt(0)
	s_barrier
	ds_write_b128 v57, v[46:49]
	ds_write_b128 v57, v[42:45] offset:16
	ds_write_b128 v57, v[38:41] offset:20480
	ds_write_b128 v57, v[34:37] offset:20496
	s_waitcnt lgkmcnt(0)
	s_mov_b32 s22, 0x100
	v_lshl_add_u64 v[124:125], v[50:51], 0, s[22:23]
	v_lshl_add_u64 v[126:127], v[52:53], 0, s[22:23]
	global_load_dwordx4 v[46:49], v[124:125], off
	global_load_dwordx4 v[42:45], v[124:125], off offset:16
	global_load_dwordx4 v[38:41], v[126:127], off
	global_load_dwordx4 v[34:37], v[126:127], off offset:16
	s_barrier
	s_mov_b32 s6, 0
	s_waitcnt vmcnt(4)
	ds_write_b128 v57, v[84:87] offset:40960
	ds_write_b128 v57, v[80:83] offset:40976
	ds_write_b128 v57, v[76:79] offset:61440
	ds_write_b128 v57, v[72:75] offset:61456
	ds_read_b128 v[60:63], v59 offset:20480
	ds_read_b128 v[64:67], v58
	ds_read_b128 v[68:71], v59 offset:23040
	ds_read_b128 v[88:91], v58 offset:2560
	ds_read_b128 v[92:95], v58 offset:5120
	ds_read_b128 v[96:99], v58 offset:7680
	ds_read_b128 v[100:103], v59 offset:20544
	ds_read_b128 v[104:107], v58 offset:64
	ds_read_b128 v[108:111], v59 offset:23104
	ds_read_b128 v[112:115], v58 offset:2624
	ds_read_b128 v[116:119], v58 offset:5184
	ds_read_b128 v[120:123], v58 offset:7744
	s_add_i32 s14, s6, 3
	s_add_i32 s22, s64, -1
	s_min_u32 s14, s14, s22
	s_lshl_b32 s22, s14, 7
	s_waitcnt lgkmcnt(12)
	v_lshl_add_u64 v[124:125], v[50:51], 0, s[22:23]
	v_lshl_add_u64 v[126:127], v[52:53], 0, s[22:23]
	global_load_dwordx4 v[84:87], v[124:125], off
	global_load_dwordx4 v[80:83], v[124:125], off offset:16
	global_load_dwordx4 v[76:79], v[126:127], off
	global_load_dwordx4 v[72:75], v[126:127], off offset:16
	s_waitcnt lgkmcnt(0)
	s_barrier
.Lsrt_loop:
	s_waitcnt vmcnt(4)
	ds_write_b128 v57, v[46:49]
	ds_write_b128 v57, v[42:45] offset:16
	ds_write_b128 v57, v[38:41] offset:20480
	ds_write_b128 v57, v[34:37] offset:20496
	ds_read_b128 v[176:179], v59 offset:61440
	ds_read_b128 v[180:183], v58 offset:40960
	ds_read_b128 v[184:187], v59 offset:64000
	ds_read_b128 v[188:191], v58 offset:43520
	ds_read_b128 v[192:195], v58 offset:46080
	ds_read_b128 v[196:199], v58 offset:48640
	ds_read_b128 v[200:203], v59 offset:61504
	ds_read_b128 v[204:207], v58 offset:41024
	ds_read_b128 v[208:211], v59 offset:64064
	ds_read_b128 v[224:227], v58 offset:43584
	ds_read_b128 v[228:231], v58 offset:46144
	ds_read_b128 v[232:235], v58 offset:48704
	s_add_i32 s14, s6, 4
	s_add_i32 s22, s64, -1
	s_min_u32 s14, s14, s22
	s_lshl_b32 s22, s14, 7
	v_mfma_f32_16x16x32_bf16 v[30:33], v[60:63], v[64:67], v[30:33]
	v_mfma_f32_16x16x32_bf16 v[14:17], v[68:71], v[64:67], v[14:17]
	v_mfma_f32_16x16x32_bf16 v[26:29], v[60:63], v[88:91], v[26:29]
	v_mfma_f32_16x16x32_bf16 v[10:13], v[68:71], v[88:91], v[10:13]
	v_mfma_f32_16x16x32_bf16 v[22:25], v[60:63], v[92:95], v[22:25]
	v_mfma_f32_16x16x32_bf16 v[6:9], v[68:71], v[92:95], v[6:9]
	v_mfma_f32_16x16x32_bf16 v[18:21], v[60:63], v[96:99], v[18:21]
	v_mfma_f32_16x16x32_bf16 v[2:5], v[68:71], v[96:99], v[2:5]
	s_waitcnt lgkmcnt(12)
	v_lshl_add_u64 v[124:125], v[50:51], 0, s[22:23]
	v_lshl_add_u64 v[126:127], v[52:53], 0, s[22:23]
	global_load_dwordx4 v[46:49], v[124:125], off
	global_load_dwordx4 v[42:45], v[124:125], off offset:16
	global_load_dwordx4 v[38:41], v[126:127], off
	global_load_dwordx4 v[34:37], v[126:127], off offset:16
	v_mfma_f32_16x16x32_bf16 v[30:33], v[100:103], v[104:107], v[30:33]
	v_mfma_f32_16x16x32_bf16 v[14:17], v[108:111], v[104:107], v[14:17]
	v_mfma_f32_16x16x32_bf16 v[26:29], v[100:103], v[112:115], v[26:29]
	v_mfma_f32_16x16x32_bf16 v[10:13], v[108:111], v[112:115], v[10:13]
	v_mfma_f32_16x16x32_bf16 v[22:25], v[100:103], v[116:119], v[22:25]
	v_mfma_f32_16x16x32_bf16 v[6:9], v[108:111], v[116:119], v[6:9]
	v_mfma_f32_16x16x32_bf16 v[18:21], v[100:103], v[120:123], v[18:21]
	v_mfma_f32_16x16x32_bf16 v[2:5], v[108:111], v[120:123], v[2:5]
	s_waitcnt lgkmcnt(0)
	s_barrier
	s_waitcnt vmcnt(4)
	ds_write_b128 v57, v[84:87] offset:40960
	ds_write_b128 v57, v[80:83] offset:40976
	ds_write_b128 v57, v[76:79] offset:61440
	ds_write_b128 v57, v[72:75] offset:61456
	ds_read_b128 v[60:63], v59 offset:20480
	ds_read_b128 v[64:67], v58
	ds_read_b128 v[68:71], v59 offset:23040
	ds_read_b128 v[88:91], v58 offset:2560
	ds_read_b128 v[92:95], v58 offset:5120
	ds_read_b128 v[96:99], v58 offset:7680
	ds_read_b128 v[100:103], v59 offset:20544
	ds_read_b128 v[104:107], v58 offset:64
	ds_read_b128 v[108:111], v59 offset:23104
	ds_read_b128 v[112:115], v58 offset:2624
	ds_read_b128 v[116:119], v58 offset:5184
	ds_read_b128 v[120:123], v58 offset:7744
	s_add_i32 s14, s6, 5
	s_add_i32 s22, s64, -1
	s_min_u32 s14, s14, s22
	s_lshl_b32 s22, s14, 7
	v_mfma_f32_16x16x32_bf16 v[30:33], v[176:179], v[180:183], v[30:33]
	v_mfma_f32_16x16x32_bf16 v[14:17], v[184:187], v[180:183], v[14:17]
	v_mfma_f32_16x16x32_bf16 v[26:29], v[176:179], v[188:191], v[26:29]
	v_mfma_f32_16x16x32_bf16 v[10:13], v[184:187], v[188:191], v[10:13]
	v_mfma_f32_16x16x32_bf16 v[22:25], v[176:179], v[192:195], v[22:25]
	v_mfma_f32_16x16x32_bf16 v[6:9], v[184:187], v[192:195], v[6:9]
	v_mfma_f32_16x16x32_bf16 v[18:21], v[176:179], v[196:199], v[18:21]
	v_mfma_f32_16x16x32_bf16 v[2:5], v[184:187], v[196:199], v[2:5]
	s_waitcnt lgkmcnt(12)
	v_lshl_add_u64 v[124:125], v[50:51], 0, s[22:23]
	v_lshl_add_u64 v[126:127], v[52:53], 0, s[22:23]
	global_load_dwordx4 v[84:87], v[124:125], off
	global_load_dwordx4 v[80:83], v[124:125], off offset:16
	global_load_dwordx4 v[76:79], v[126:127], off
	global_load_dwordx4 v[72:75], v[126:127], off offset:16
	v_mfma_f32_16x16x32_bf16 v[30:33], v[200:203], v[204:207], v[30:33]
	v_mfma_f32_16x16x32_bf16 v[14:17], v[208:211], v[204:207], v[14:17]
	v_mfma_f32_16x16x32_bf16 v[26:29], v[200:203], v[224:227], v[26:29]
	v_mfma_f32_16x16x32_bf16 v[10:13], v[208:211], v[224:227], v[10:13]
	v_mfma_f32_16x16x32_bf16 v[22:25], v[200:203], v[228:231], v[22:25]
	v_mfma_f32_16x16x32_bf16 v[6:9], v[208:211], v[228:231], v[6:9]
	v_mfma_f32_16x16x32_bf16 v[18:21], v[200:203], v[232:235], v[18:21]
	v_mfma_f32_16x16x32_bf16 v[2:5], v[208:211], v[232:235], v[2:5]
	s_waitcnt lgkmcnt(0)
	s_barrier
	s_add_i32 s6, s6, 2
	s_cmp_lt_u32 s6, s64
	s_cbranch_scc1 .Lsrt_loop
	s_waitcnt vmcnt(0)
